# attention epilogue: v_permlane16_swap pairs -> dwordx4 output stores (2 instead of 4 per q tile); sample units load all gates up front as 2 dwordx4
# speedup vs baseline: 1.0171x; 1.0046x over previous
.LBB0_558:
	v_and_b32_e32 v38, 64, v208
	v_xor_b32_e32 v37, 16, v208
	v_add_u32_e32 v38, 64, v38
	v_cmp_lt_i32_e32 vcc, v37, v38
	v_sub_f32_e32 v0, v39, v0
	v_fmac_f32_e32 v0, 0x43030000, v102
	v_cndmask_b32_e32 v37, v208, v37, vcc
	v_lshlrev_b32_e32 v173, 2, v37
	v_cndmask_b32_e64 v0, v214, v0, s[56:57]
	v_max_f32_e32 v37, v178, v178
	v_max_f32_e32 v37, v37, v0
	ds_bpermute_b32 v39, v173, v37
	v_xor_b32_e32 v40, 32, v208
	v_cmp_lt_i32_e32 vcc, v40, v38
	s_waitcnt vmcnt(0)
	v_mul_f32_e32 v67, 0x3fb8aa3b, v1
	v_add_u32_e32 v93, 0x5800, v171
	v_cndmask_b32_e32 v38, v208, v40, vcc
	v_lshlrev_b32_e32 v174, 2, v38
	s_waitcnt lgkmcnt(0)
	v_max_f32_e32 v38, v39, v39
	v_max_f32_e32 v37, v37, v38
	ds_bpermute_b32 v38, v174, v37
	s_mov_b32 s92, s50
	s_movk_i32 s93, 0x4400
	s_mov_b32 s94, 0xc2fc0000
	v_lshl_add_u64 v[64:65], s[44:45], 1, v[86:87]
	s_waitcnt lgkmcnt(0)
	v_max3_f32 v52, v37, v38, v67
	v_sub_f32_e32 v1, v3, v52
	v_exp_f32_e32 v1, v1
	v_sub_f32_e32 v3, v36, v52
	v_exp_f32_e32 v3, v3
	v_sub_f32_e32 v36, v91, v52
	v_exp_f32_e32 v41, v36
	v_sub_f32_e32 v37, v89, v52
	v_exp_f32_e32 v42, v37
	v_sub_f32_e32 v37, v48, v52
	v_add_f32_e32 v36, 0, v1
	v_exp_f32_e32 v43, v37
	v_sub_f32_e32 v37, v49, v52
	v_add_f32_e32 v36, v3, v36
	v_exp_f32_e32 v48, v37
	v_sub_f32_e32 v37, v72, v52
	v_add_f32_e32 v36, v41, v36
	v_exp_f32_e32 v49, v37
	v_sub_f32_e32 v37, v73, v52
	v_add_f32_e32 v36, v42, v36
	v_exp_f32_e32 v50, v37
	v_sub_f32_e32 v37, v74, v52
	v_add_f32_e32 v36, v43, v36
	v_exp_f32_e32 v55, v37
	v_sub_f32_e32 v37, v75, v52
	v_add_f32_e32 v36, v48, v36
	v_exp_f32_e32 v60, v37
	v_sub_f32_e32 v37, v114, v52
	v_add_f32_e32 v36, v49, v36
	v_exp_f32_e32 v61, v37
	v_sub_f32_e32 v37, v115, v52
	v_add_f32_e32 v36, v50, v36
	v_exp_f32_e32 v62, v37
	v_sub_f32_e32 v37, v116, v52
	v_add_f32_e32 v36, v55, v36
	v_exp_f32_e32 v63, v37
	v_sub_f32_e32 v37, v117, v52
	v_add_f32_e32 v36, v60, v36
	v_exp_f32_e32 v66, v37
	v_sub_f32_e32 v37, v118, v52
	v_add_f32_e32 v36, v61, v36
	v_exp_f32_e32 v68, v37
	v_sub_f32_e32 v37, v119, v52
	v_add_f32_e32 v36, v62, v36
	v_exp_f32_e32 v69, v37
	v_sub_f32_e32 v37, v120, v52
	v_add_f32_e32 v36, v63, v36
	v_exp_f32_e32 v70, v37
	v_sub_f32_e32 v37, v121, v52
	v_add_f32_e32 v36, v66, v36
	v_exp_f32_e32 v71, v37
	v_sub_f32_e32 v37, v122, v52
	v_add_f32_e32 v36, v68, v36
	v_exp_f32_e32 v72, v37
	v_sub_f32_e32 v37, v123, v52
	v_add_f32_e32 v36, v69, v36
	v_exp_f32_e32 v73, v37
	v_sub_f32_e32 v37, v124, v52
	v_add_f32_e32 v36, v70, v36
	v_exp_f32_e32 v74, v37
	v_sub_f32_e32 v37, v125, v52
	v_add_f32_e32 v36, v71, v36
	v_exp_f32_e32 v75, v37
	v_sub_f32_e32 v37, v126, v52
	v_add_f32_e32 v36, v72, v36
	v_exp_f32_e32 v114, v37
	v_sub_f32_e32 v37, v127, v52
	v_add_f32_e32 v36, v73, v36
	v_exp_f32_e32 v115, v37
	v_sub_f32_e32 v37, v128, v52
	v_add_f32_e32 v36, v74, v36
	v_exp_f32_e32 v116, v37
	v_sub_f32_e32 v37, v129, v52
	v_add_f32_e32 v36, v75, v36
	v_exp_f32_e32 v117, v37
	v_sub_f32_e32 v37, v130, v52
	v_add_f32_e32 v36, v114, v36
	v_exp_f32_e32 v118, v37
	v_sub_f32_e32 v37, v131, v52
	v_add_f32_e32 v36, v115, v36
	v_exp_f32_e32 v119, v37
	v_sub_f32_e32 v37, v132, v52
	v_add_f32_e32 v36, v116, v36
	v_exp_f32_e32 v120, v37
	v_sub_f32_e32 v37, v133, v52
	v_add_f32_e32 v36, v117, v36
	v_exp_f32_e32 v121, v37
	v_sub_f32_e32 v37, v134, v52
	v_add_f32_e32 v36, v118, v36
	v_exp_f32_e32 v122, v37
	v_sub_f32_e32 v37, v135, v52
	v_add_f32_e32 v36, v119, v36
	v_exp_f32_e32 v123, v37
	v_sub_f32_e32 v37, v175, v52
	v_add_f32_e32 v36, v120, v36
	v_exp_f32_e32 v125, v37
	v_sub_f32_e32 v37, v177, v52
	v_add_f32_e32 v36, v121, v36
	v_exp_f32_e32 v126, v37
	v_sub_f32_e32 v37, v176, v52
	v_add_f32_e32 v36, v122, v36
	v_exp_f32_e32 v127, v37
	v_sub_f32_e32 v0, v0, v52
	v_add_f32_e32 v36, v123, v36
	v_exp_f32_e32 v128, v0
	v_add_f32_e32 v36, v125, v36
	v_add_f32_e32 v36, v126, v36
	v_add_u32_e32 v124, 0x6800, v171
	v_add_u32_e32 v89, 0x8000, v171
	v_add_u32_e32 v91, 0x9800, v171
	v_add_f32_e32 v53, v127, v36
	ds_read2_b64 v[36:39], v93 offset0:64 offset1:68
	v_cvt_pk_bf16_f32 v41, v41, v42
	ds_read2_b64 v[44:47], v124 offset0:224 offset1:228
	v_cvt_pk_bf16_f32 v42, v43, v48
	v_cvt_pk_bf16_f32 v43, v49, v50
	ds_read2_b64 v[48:51], v89 offset0:128 offset1:132
	ds_read2_b64 v[56:59], v91 offset0:32 offset1:36
	v_add_f32_e32 v0, v128, v53
	v_cvt_pk_bf16_f32 v40, v1, v3
	ds_bpermute_b32 v1, v173, v0
	s_waitcnt lgkmcnt(0)
	v_add_f32_e32 v53, v0, v1
	ds_bpermute_b32 v54, v174, v53
	v_mfma_f32_16x16x32_bf16 v[36:39], v[36:39], v[40:43], 0
	v_mfma_f32_16x16x32_bf16 v[44:47], v[44:47], v[40:43], 0
	v_mfma_f32_16x16x32_bf16 v[48:51], v[48:51], v[40:43], 0
	v_mfma_f32_16x16x32_bf16 v[40:43], v[56:59], v[40:43], 0
	v_cvt_pk_bf16_f32 v56, v55, v60
	v_cvt_pk_bf16_f32 v57, v61, v62
	v_cvt_pk_bf16_f32 v58, v63, v66
	ds_read2_b64 v[60:63], v93 offset0:72 offset1:76
	v_cvt_pk_bf16_f32 v59, v68, v69
	s_waitcnt lgkmcnt(0)
	s_nop 0
	v_mfma_f32_16x16x32_bf16 v[36:39], v[60:63], v[56:59], v[36:39]
	ds_read2_b64 v[60:63], v124 offset0:232 offset1:236
	s_waitcnt lgkmcnt(0)
	v_mfma_f32_16x16x32_bf16 v[44:47], v[60:63], v[56:59], v[44:47]
	ds_read2_b64 v[60:63], v89 offset0:136 offset1:140
	s_waitcnt lgkmcnt(0)
	v_mfma_f32_16x16x32_bf16 v[48:51], v[60:63], v[56:59], v[48:51]
	ds_read2_b64 v[60:63], v91 offset0:40 offset1:44
	s_waitcnt lgkmcnt(0)
	v_mfma_f32_16x16x32_bf16 v[40:43], v[60:63], v[56:59], v[40:43]
	ds_read2_b64 v[60:63], v93 offset0:80 offset1:84
	v_cvt_pk_bf16_f32 v56, v70, v71
	v_cvt_pk_bf16_f32 v57, v72, v73
	v_cvt_pk_bf16_f32 v58, v74, v75
	v_cvt_pk_bf16_f32 v59, v114, v115
	s_waitcnt lgkmcnt(0)
	s_nop 0
	v_mfma_f32_16x16x32_bf16 v[36:39], v[60:63], v[56:59], v[36:39]
	ds_read2_b64 v[60:63], v124 offset0:240 offset1:244
	s_waitcnt lgkmcnt(0)
	v_mfma_f32_16x16x32_bf16 v[44:47], v[60:63], v[56:59], v[44:47]
	ds_read2_b64 v[60:63], v89 offset0:144 offset1:148
	s_waitcnt lgkmcnt(0)
	v_mfma_f32_16x16x32_bf16 v[48:51], v[60:63], v[56:59], v[48:51]
	ds_read2_b64 v[60:63], v91 offset0:48 offset1:52
	s_waitcnt lgkmcnt(0)
	v_mfma_f32_16x16x32_bf16 v[40:43], v[60:63], v[56:59], v[40:43]
	ds_read2_b64 v[60:63], v93 offset0:88 offset1:92
	v_cvt_pk_bf16_f32 v56, v116, v117
	v_cvt_pk_bf16_f32 v57, v118, v119
	v_cvt_pk_bf16_f32 v58, v120, v121
	v_cvt_pk_bf16_f32 v59, v122, v123
	s_waitcnt lgkmcnt(0)
	s_nop 0
	v_mfma_f32_16x16x32_bf16 v[36:39], v[60:63], v[56:59], v[36:39]
	ds_read2_b64 v[60:63], v124 offset0:248 offset1:252
	s_waitcnt lgkmcnt(0)
	v_mfma_f32_16x16x32_bf16 v[44:47], v[60:63], v[56:59], v[44:47]
	ds_read2_b64 v[60:63], v89 offset0:152 offset1:156
	s_waitcnt lgkmcnt(0)
	v_mfma_f32_16x16x32_bf16 v[60:63], v[60:63], v[56:59], v[48:51]
	s_nop 2
	ds_read2_b64 v[48:51], v91 offset0:56 offset1:60
	s_waitcnt lgkmcnt(0)
	v_mfma_f32_16x16x32_bf16 v[56:59], v[48:51], v[56:59], v[40:43]
	s_nop 2
	ds_read2_b64 v[40:43], v93 offset0:96 offset1:100
	v_cvt_pk_bf16_f32 v0, v125, v126
	v_cvt_pk_bf16_f32 v1, v127, v128
	v_mov_b32_e32 v3, v2
	v_add_u32_e32 v125, 0x7000, v171
	s_waitcnt lgkmcnt(0)
	v_mfma_f32_16x16x32_bf16 v[48:51], v[40:43], v[0:3], v[36:39]
	s_nop 2
	ds_read2_b64 v[36:39], v125 offset1:4
	s_waitcnt lgkmcnt(0)
	v_mfma_f32_16x16x32_bf16 v[44:47], v[36:39], v[0:3], v[44:47]
	ds_read2_b64 v[36:39], v89 offset0:160 offset1:164
	s_waitcnt lgkmcnt(0)
	v_mfma_f32_16x16x32_bf16 v[40:43], v[36:39], v[0:3], v[60:63]
	ds_read2_b64 v[36:39], v91 offset0:64 offset1:68
	s_waitcnt lgkmcnt(0)
	v_mfma_f32_16x16x32_bf16 v[36:39], v[36:39], v[0:3], v[56:59]
	v_or_b32_e32 v0, s70, v103
	s_movk_i32 s0, 0x810
	v_cmp_gt_i32_e32 vcc, s0, v0
	s_and_saveexec_b64 s[0:1], vcc
	s_cbranch_execz .LBB0_560
	v_sub_f32_e32 v0, v67, v52
	v_exp_f32_e32 v0, v0
	v_add_f32_e32 v1, v53, v54
	v_add_f32_e32 v3, v0, v1
	v_div_scale_f32 v52, s[4:5], v3, v3, 1.0
	v_rcp_f32_e32 v53, v52
	v_div_scale_f32 v54, vcc, 1.0, v3, 1.0
	v_lshl_add_u64 v[0:1], v[64:65], 0, v[112:113]
	v_fma_f32 v55, -v52, v53, 1.0
	v_fmac_f32_e32 v53, v55, v53
	v_mul_f32_e32 v55, v54, v53
	v_fma_f32 v56, -v52, v55, v54
	v_fmac_f32_e32 v55, v56, v53
	v_fma_f32 v52, -v52, v55, v54
	v_div_fmas_f32 v52, v52, v53, v55
	v_div_fixup_f32 v52, v52, v3, 1.0
	v_pk_mul_f32 v[48:49], v[52:53], v[48:49] op_sel_hi:[0,1]
	v_pk_mul_f32 v[50:51], v[52:53], v[50:51] op_sel_hi:[0,1]
	v_lshlrev_b32_e32 v54, 16, v110
	v_and_b32_e32 v55, 0xffff0000, v110
	v_pk_mul_f32 v[48:49], v[48:49], v[54:55]
	v_lshlrev_b32_e32 v54, 16, v111
	v_and_b32_e32 v55, 0xffff0000, v111
	v_pk_mul_f32 v[50:51], v[50:51], v[54:55]
	v_cvt_pk_bf16_f32 v48, v48, v49
	v_cvt_pk_bf16_f32 v49, v50, v51
	v_pk_mul_f32 v[44:45], v[52:53], v[44:45] op_sel_hi:[0,1]
	v_pk_mul_f32 v[46:47], v[52:53], v[46:47] op_sel_hi:[0,1]
	v_lshlrev_b32_e32 v54, 16, v108
	v_and_b32_e32 v55, 0xffff0000, v108
	v_pk_mul_f32 v[44:45], v[44:45], v[54:55]
	v_lshlrev_b32_e32 v54, 16, v109
	v_and_b32_e32 v55, 0xffff0000, v109
	v_pk_mul_f32 v[46:47], v[46:47], v[54:55]
	v_cvt_pk_bf16_f32 v50, v44, v45
	v_cvt_pk_bf16_f32 v51, v46, v47
	v_mbcnt_lo_u32_b32 v54, -1, 0
	v_mbcnt_hi_u32_b32 v54, -1, v54
	v_and_b32_e32 v54, 16, v54
	v_lshrrev_b32_e32 v55, 1, v54
	v_add_u32_e32 v54, v54, v55
	v_mov_b32_e32 v55, 0
	v_lshl_add_u64 v[0:1], v[54:55], 0, v[0:1]
	v_permlane16_swap_b32 v48, v50
	v_permlane16_swap_b32 v49, v51
	global_store_dwordx4 v[0:1], v[48:51], off
	v_pk_mul_f32 v[40:41], v[52:53], v[40:41] op_sel_hi:[0,1]
	v_pk_mul_f32 v[42:43], v[52:53], v[42:43] op_sel_hi:[0,1]
	v_lshlrev_b32_e32 v44, 16, v106
	v_and_b32_e32 v45, 0xffff0000, v106
	v_pk_mul_f32 v[40:41], v[40:41], v[44:45]
	v_lshlrev_b32_e32 v44, 16, v107
	v_and_b32_e32 v45, 0xffff0000, v107
	v_pk_mul_f32 v[42:43], v[42:43], v[44:45]
	v_cvt_pk_bf16_f32 v40, v40, v41
	v_cvt_pk_bf16_f32 v41, v42, v43
	v_pk_mul_f32 v[36:37], v[52:53], v[36:37] op_sel_hi:[0,1]
	v_pk_mul_f32 v[38:39], v[52:53], v[38:39] op_sel_hi:[0,1]
	v_lshlrev_b32_e32 v44, 16, v104
	v_and_b32_e32 v45, 0xffff0000, v104
	v_pk_mul_f32 v[36:37], v[36:37], v[44:45]
	v_lshlrev_b32_e32 v44, 16, v105
	v_and_b32_e32 v45, 0xffff0000, v105
	v_pk_mul_f32 v[38:39], v[38:39], v[44:45]
	v_cvt_pk_bf16_f32 v42, v36, v37
	v_cvt_pk_bf16_f32 v43, v38, v39
	s_nop 1
	v_permlane16_swap_b32 v40, v42
	v_permlane16_swap_b32 v41, v43
	global_store_dwordx4 v[0:1], v[40:43], off offset:64
	s_nop 1

.LBB0_564:
	v_sub_f32_e32 v3, v31, v66
	v_fmac_f32_e32 v3, 0x43130000, v102
	v_cndmask_b32_e64 v28, v214, v3, s[0:1]
	v_max_f32_e32 v3, v132, v132
	v_max_f32_e32 v3, v3, v28
	ds_bpermute_b32 v29, v173, v3
	ds_read2_b64 v[36:39], v124 offset0:224 offset1:228
	ds_read2_b64 v[40:43], v89 offset0:128 offset1:132
	ds_read2_b64 v[44:47], v91 offset0:32 offset1:36
	s_waitcnt lgkmcnt(3)
	v_max_f32_e32 v29, v29, v29
	v_max_f32_e32 v3, v3, v29
	ds_bpermute_b32 v29, v174, v3
	s_waitcnt lgkmcnt(0)
	v_max3_f32 v3, v3, v29, v67
	v_sub_f32_e32 v29, v127, v3
	v_exp_f32_e32 v29, v29
	v_sub_f32_e32 v30, v30, v3
	v_exp_f32_e32 v30, v30
	v_sub_f32_e32 v32, v128, v3
	v_exp_f32_e32 v32, v32
	v_sub_f32_e32 v33, v126, v3
	v_exp_f32_e32 v33, v33
	v_sub_f32_e32 v34, v104, v3
	v_add_f32_e32 v31, 0, v29
	v_exp_f32_e32 v48, v34
	v_sub_f32_e32 v34, v105, v3
	v_add_f32_e32 v31, v30, v31
	v_exp_f32_e32 v49, v34
	v_sub_f32_e32 v0, v0, v3
	v_add_f32_e32 v31, v32, v31
	v_exp_f32_e32 v50, v0
	v_sub_f32_e32 v1, v1, v3
	v_add_f32_e32 v31, v33, v31
	v_exp_f32_e32 v51, v1
	v_sub_f32_e32 v1, v68, v3
	v_add_f32_e32 v31, v48, v31
	v_exp_f32_e32 v52, v1
	v_sub_f32_e32 v1, v69, v3
	v_add_f32_e32 v31, v49, v31
	v_exp_f32_e32 v53, v1
	v_sub_f32_e32 v1, v70, v3
	v_add_f32_e32 v0, v50, v31
	v_exp_f32_e32 v54, v1
	v_sub_f32_e32 v1, v71, v3
	v_add_f32_e32 v0, v51, v0
	v_exp_f32_e32 v55, v1
	v_sub_f32_e32 v1, v72, v3
	v_add_f32_e32 v0, v52, v0
	v_exp_f32_e32 v56, v1
	v_sub_f32_e32 v1, v73, v3
	v_add_f32_e32 v0, v53, v0
	v_exp_f32_e32 v57, v1
	v_sub_f32_e32 v1, v74, v3
	v_add_f32_e32 v0, v54, v0
	v_exp_f32_e32 v58, v1
	v_sub_f32_e32 v1, v75, v3
	v_add_f32_e32 v0, v55, v0
	v_exp_f32_e32 v59, v1
	v_sub_f32_e32 v1, v106, v3
	v_add_f32_e32 v0, v56, v0
	v_exp_f32_e32 v60, v1
	v_sub_f32_e32 v1, v107, v3
	v_add_f32_e32 v0, v57, v0
	v_exp_f32_e32 v61, v1
	v_sub_f32_e32 v1, v110, v3
	v_add_f32_e32 v0, v58, v0
	v_exp_f32_e32 v62, v1
	v_sub_f32_e32 v1, v111, v3
	v_add_f32_e32 v0, v59, v0
	v_exp_f32_e32 v63, v1
	v_sub_f32_e32 v1, v112, v3
	v_add_f32_e32 v0, v60, v0
	v_exp_f32_e32 v66, v1
	v_sub_f32_e32 v1, v113, v3
	v_add_f32_e32 v0, v61, v0
	v_exp_f32_e32 v68, v1
	v_sub_f32_e32 v1, v114, v3
	v_add_f32_e32 v0, v62, v0
	v_exp_f32_e32 v69, v1
	v_sub_f32_e32 v1, v115, v3
	v_add_f32_e32 v0, v63, v0
	v_exp_f32_e32 v70, v1
	v_sub_f32_e32 v1, v116, v3
	v_add_f32_e32 v0, v66, v0
	v_exp_f32_e32 v71, v1
	v_sub_f32_e32 v1, v117, v3
	v_add_f32_e32 v0, v68, v0
	v_exp_f32_e32 v72, v1
	v_sub_f32_e32 v1, v118, v3
	v_add_f32_e32 v0, v69, v0
	v_exp_f32_e32 v73, v1
	v_sub_f32_e32 v1, v119, v3
	v_add_f32_e32 v0, v70, v0
	v_exp_f32_e32 v74, v1
	v_sub_f32_e32 v1, v120, v3
	v_add_f32_e32 v0, v71, v0
	v_exp_f32_e32 v75, v1
	v_sub_f32_e32 v1, v121, v3
	v_add_f32_e32 v0, v72, v0
	v_exp_f32_e32 v102, v1
	v_sub_f32_e32 v1, v122, v3
	v_add_f32_e32 v0, v73, v0
	v_exp_f32_e32 v104, v1
	v_sub_f32_e32 v1, v123, v3
	v_add_f32_e32 v0, v74, v0
	v_exp_f32_e32 v105, v1
	v_sub_f32_e32 v1, v131, v3
	v_add_f32_e32 v0, v75, v0
	v_exp_f32_e32 v106, v1
	v_sub_f32_e32 v1, v129, v3
	v_add_f32_e32 v0, v102, v0
	v_exp_f32_e32 v107, v1
	v_sub_f32_e32 v1, v130, v3
	v_add_f32_e32 v0, v104, v0
	v_exp_f32_e32 v108, v1
	v_sub_f32_e32 v1, v28, v3
	v_add_f32_e32 v0, v105, v0
	v_exp_f32_e32 v109, v1
	v_add_f32_e32 v0, v106, v0
	v_add_f32_e32 v0, v107, v0
	v_add_f32_e32 v0, v108, v0
	v_cvt_pk_bf16_f32 v31, v32, v33
	ds_read2_b64 v[32:35], v93 offset0:64 offset1:68
	v_add_f32_e32 v0, v109, v0
	ds_bpermute_b32 v1, v173, v0
	v_cvt_pk_bf16_f32 v30, v29, v30
	v_mov_b32_e32 v28, v2
	v_mov_b32_e32 v29, v2
	s_waitcnt lgkmcnt(0)
	v_add_f32_e32 v0, v0, v1
	ds_bpermute_b32 v1, v174, v0
	v_mfma_f32_16x16x32_bf16 v[32:35], v[32:35], v[28:31], 0
	v_mfma_f32_16x16x32_bf16 v[36:39], v[36:39], v[28:31], 0
	v_mfma_f32_16x16x32_bf16 v[40:43], v[40:43], v[28:31], 0
	v_mfma_f32_16x16x32_bf16 v[28:31], v[44:47], v[28:31], 0
	v_cvt_pk_bf16_f32 v44, v48, v49
	v_cvt_pk_bf16_f32 v45, v50, v51
	ds_read2_b64 v[48:51], v93 offset0:72 offset1:76
	v_cvt_pk_bf16_f32 v46, v52, v53
	v_cvt_pk_bf16_f32 v47, v54, v55
	s_waitcnt lgkmcnt(0)
	s_nop 0
	v_mfma_f32_16x16x32_bf16 v[32:35], v[48:51], v[44:47], v[32:35]
	ds_read2_b64 v[48:51], v124 offset0:232 offset1:236
	s_waitcnt lgkmcnt(0)
	v_mfma_f32_16x16x32_bf16 v[36:39], v[48:51], v[44:47], v[36:39]
	ds_read2_b64 v[48:51], v89 offset0:136 offset1:140
	s_waitcnt lgkmcnt(0)
	v_mfma_f32_16x16x32_bf16 v[40:43], v[48:51], v[44:47], v[40:43]
	ds_read2_b64 v[48:51], v91 offset0:40 offset1:44
	s_waitcnt lgkmcnt(0)
	v_mfma_f32_16x16x32_bf16 v[28:31], v[48:51], v[44:47], v[28:31]
	ds_read2_b64 v[48:51], v93 offset0:80 offset1:84
	v_cvt_pk_bf16_f32 v44, v56, v57
	v_cvt_pk_bf16_f32 v45, v58, v59
	v_cvt_pk_bf16_f32 v46, v60, v61
	v_cvt_pk_bf16_f32 v47, v62, v63
	s_waitcnt lgkmcnt(0)
	s_nop 0
	v_mfma_f32_16x16x32_bf16 v[32:35], v[48:51], v[44:47], v[32:35]
	ds_read2_b64 v[48:51], v124 offset0:240 offset1:244
	s_waitcnt lgkmcnt(0)
	v_mfma_f32_16x16x32_bf16 v[36:39], v[48:51], v[44:47], v[36:39]
	ds_read2_b64 v[48:51], v89 offset0:144 offset1:148
	s_waitcnt lgkmcnt(0)
	v_mfma_f32_16x16x32_bf16 v[40:43], v[48:51], v[44:47], v[40:43]
	ds_read2_b64 v[48:51], v91 offset0:48 offset1:52
	s_waitcnt lgkmcnt(0)
	v_mfma_f32_16x16x32_bf16 v[28:31], v[48:51], v[44:47], v[28:31]
	ds_read2_b64 v[48:51], v93 offset0:88 offset1:92
	v_cvt_pk_bf16_f32 v44, v66, v68
	v_cvt_pk_bf16_f32 v45, v69, v70
	v_cvt_pk_bf16_f32 v46, v71, v72
	v_cvt_pk_bf16_f32 v47, v73, v74
	s_waitcnt lgkmcnt(0)
	s_nop 0
	v_mfma_f32_16x16x32_bf16 v[32:35], v[48:51], v[44:47], v[32:35]
	ds_read2_b64 v[48:51], v124 offset0:248 offset1:252
	s_waitcnt lgkmcnt(0)
	v_mfma_f32_16x16x32_bf16 v[36:39], v[48:51], v[44:47], v[36:39]
	ds_read2_b64 v[48:51], v89 offset0:152 offset1:156
	s_waitcnt lgkmcnt(0)
	v_mfma_f32_16x16x32_bf16 v[48:51], v[48:51], v[44:47], v[40:43]
	s_nop 2
	ds_read2_b64 v[40:43], v91 offset0:56 offset1:60
	s_waitcnt lgkmcnt(0)
	v_mfma_f32_16x16x32_bf16 v[28:31], v[40:43], v[44:47], v[28:31]
	ds_read2_b64 v[40:43], v93 offset0:96 offset1:100
	v_cvt_pk_bf16_f32 v44, v75, v102
	v_cvt_pk_bf16_f32 v45, v104, v105
	v_cvt_pk_bf16_f32 v46, v106, v107
	v_cvt_pk_bf16_f32 v47, v108, v109
	s_waitcnt lgkmcnt(0)
	s_nop 0
	v_mfma_f32_16x16x32_bf16 v[40:43], v[40:43], v[44:47], v[32:35]
	s_nop 2
	ds_read2_b64 v[32:35], v125 offset1:4
	s_waitcnt lgkmcnt(0)
	v_mfma_f32_16x16x32_bf16 v[36:39], v[32:35], v[44:47], v[36:39]
	ds_read2_b64 v[32:35], v89 offset0:160 offset1:164
	s_waitcnt lgkmcnt(0)
	v_mfma_f32_16x16x32_bf16 v[32:35], v[32:35], v[44:47], v[48:51]
	s_nop 2
	ds_read2_b64 v[48:51], v91 offset0:64 offset1:68
	s_waitcnt lgkmcnt(0)
	v_mfma_f32_16x16x32_bf16 v[28:31], v[48:51], v[44:47], v[28:31]
	v_or_b32_e32 v44, s70, v153
	s_movk_i32 s0, 0x810
	v_cmp_gt_i32_e32 vcc, s0, v44
	s_and_saveexec_b64 s[0:1], vcc
	s_cbranch_execz .LBB0_547
	v_sub_f32_e32 v3, v67, v3
	v_exp_f32_e32 v3, v3
	v_add_f32_e32 v0, v0, v1
	v_and_b32_e32 v47, 0xffff0000, v100
	v_add_f32_e32 v0, v3, v0
	v_div_scale_f32 v1, s[4:5], v0, v0, 1.0
	v_rcp_f32_e32 v3, v1
	s_nop 0
	v_fma_f32 v44, -v1, v3, 1.0
	v_fmac_f32_e32 v3, v44, v3
	v_div_scale_f32 v44, vcc, 1.0, v0, 1.0
	v_mul_f32_e32 v45, v44, v3
	v_fma_f32 v46, -v1, v45, v44
	v_fmac_f32_e32 v45, v46, v3
	v_fma_f32 v1, -v1, v45, v44
	v_div_fmas_f32 v1, v1, v3, v45
	v_div_fixup_f32 v0, v1, v0, 1.0
	v_add_u32_e32 v44, s60, v153
	v_ashrrev_i32_e32 v45, 31, v44
	v_lshlrev_b64 v[44:45], 13, v[44:45]
	v_lshl_add_u64 v[44:45], v[64:65], 0, v[44:45]
	v_pk_mul_f32 v[40:41], v[0:1], v[40:41] op_sel_hi:[0,1]
	v_pk_mul_f32 v[42:43], v[0:1], v[42:43] op_sel_hi:[0,1]
	v_lshlrev_b32_e32 v46, 16, v100
	v_and_b32_e32 v47, 0xffff0000, v100
	v_pk_mul_f32 v[40:41], v[40:41], v[46:47]
	v_lshlrev_b32_e32 v46, 16, v101
	v_and_b32_e32 v47, 0xffff0000, v101
	v_pk_mul_f32 v[42:43], v[42:43], v[46:47]
	v_cvt_pk_bf16_f32 v40, v40, v41
	v_cvt_pk_bf16_f32 v41, v42, v43
	v_pk_mul_f32 v[36:37], v[0:1], v[36:37] op_sel_hi:[0,1]
	v_pk_mul_f32 v[38:39], v[0:1], v[38:39] op_sel_hi:[0,1]
	v_lshlrev_b32_e32 v46, 16, v98
	v_and_b32_e32 v47, 0xffff0000, v98
	v_pk_mul_f32 v[36:37], v[36:37], v[46:47]
	v_lshlrev_b32_e32 v46, 16, v99
	v_and_b32_e32 v47, 0xffff0000, v99
	v_pk_mul_f32 v[38:39], v[38:39], v[46:47]
	v_cvt_pk_bf16_f32 v42, v36, v37
	v_cvt_pk_bf16_f32 v43, v38, v39
	v_mbcnt_lo_u32_b32 v46, -1, 0
	v_mbcnt_hi_u32_b32 v46, -1, v46
	v_and_b32_e32 v46, 16, v46
	v_lshrrev_b32_e32 v47, 1, v46
	v_add_u32_e32 v46, v46, v47
	v_mov_b32_e32 v47, 0
	v_lshl_add_u64 v[44:45], v[46:47], 0, v[44:45]
	v_permlane16_swap_b32 v40, v42
	v_permlane16_swap_b32 v41, v43
	global_store_dwordx4 v[44:45], v[40:43], off
	v_pk_mul_f32 v[32:33], v[0:1], v[32:33] op_sel_hi:[0,1]
	v_pk_mul_f32 v[34:35], v[0:1], v[34:35] op_sel_hi:[0,1]
	v_pk_mul_f32 v[28:29], v[0:1], v[28:29] op_sel_hi:[0,1]
	v_pk_mul_f32 v[30:31], v[0:1], v[30:31] op_sel_hi:[0,1]
	v_lshlrev_b32_e32 v36, 16, v96
	v_and_b32_e32 v37, 0xffff0000, v96
	v_pk_mul_f32 v[32:33], v[32:33], v[36:37]
	v_lshlrev_b32_e32 v36, 16, v97
	v_and_b32_e32 v37, 0xffff0000, v97
	v_pk_mul_f32 v[34:35], v[34:35], v[36:37]
	v_cvt_pk_bf16_f32 v32, v32, v33
	v_cvt_pk_bf16_f32 v33, v34, v35
	v_lshlrev_b32_e32 v36, 16, v94
	v_and_b32_e32 v37, 0xffff0000, v94
	v_pk_mul_f32 v[28:29], v[28:29], v[36:37]
	v_lshlrev_b32_e32 v36, 16, v95
	v_and_b32_e32 v37, 0xffff0000, v95
	v_pk_mul_f32 v[30:31], v[30:31], v[36:37]
	v_cvt_pk_bf16_f32 v34, v28, v29
	v_cvt_pk_bf16_f32 v35, v30, v31
	s_nop 1
	v_permlane16_swap_b32 v32, v34
	v_permlane16_swap_b32 v33, v35
	global_store_dwordx4 v[44:45], v[32:35], off offset:64
	s_nop 1
	s_branch .LBB0_547

.LBB0_586:
	s_or_b64 exec, exec, s[8:9]
	s_lshl_b32 s7, s18, 3
	s_add_i32 s7, s7, s68
	s_add_i32 s8, s7, 1
	v_cvt_f32_i32_e32 v0, s8
	v_readlane_b32 s76, v251, 4
	v_readlane_b32 s90, v251, 18
	v_readlane_b32 s91, v251, 19
	v_mul_f32_e32 v1, 0xbe000000, v0
	v_cmp_gt_f32_e32 vcc, s94, v1
	s_and_b64 s[8:9], vcc, exec
	s_cselect_b32 s8, 0xffffffc0, 0
	v_cndmask_b32_e32 v1, 0, v213, vcc
	v_fmac_f32_e32 v1, 0xbe000000, v0
	v_exp_f32_e32 v0, v1
	v_add_u32_e32 v30, s6, v37
	v_ashrrev_i32_e32 v31, 31, v30
	v_lshlrev_b64 v[6:7], 13, v[30:31]
	v_ldexp_f32 v1, v0, s8
	s_add_i32 s8, s7, s16
	s_ashr_i32 s9, s8, 31
	s_lshl_b64 s[8:9], s[8:9], 2
	s_add_u32 s8, s90, s8
	s_addc_u32 s9, s91, s9
	s_lshl_b32 s6, s7, 6
	s_ashr_i32 s7, s6, 31
	v_lshl_add_u64 v[4:5], s[6:7], 1, v[20:21]
	v_lshl_add_u64 v[8:9], v[4:5], 0, v[6:7]
	s_waitcnt lgkmcnt(0)
	s_barrier
	global_load_dword v3, v2, s[8:9]
	global_load_dwordx4 v[4:7], v[8:9], off
	s_nop 0
	global_load_dwordx4 v[8:11], v[8:9], off offset:64
	ds_read_b128 v[12:15], v38
	ds_read_b128 v[16:19], v38 offset:64
	v_readlane_b32 s77, v251, 5
	v_readlane_b32 s78, v251, 6
	v_readlane_b32 s79, v251, 7
	v_readlane_b32 s80, v251, 8
	v_readlane_b32 s81, v251, 9
	v_readlane_b32 s82, v251, 10
	v_readlane_b32 s83, v251, 11
	v_readlane_b32 s84, v251, 12
	v_readlane_b32 s85, v251, 13
	v_readlane_b32 s86, v251, 14
	v_readlane_b32 s87, v251, 15
	v_readlane_b32 s88, v251, 16
	v_readlane_b32 s89, v251, 17
	v_mul_f32_e32 v0, 0x3fb8aa3b, v1
	s_waitcnt vmcnt(1) lgkmcnt(1)
	v_mfma_f32_16x16x32_bf16 v[12:15], v[12:15], v[4:7], 0
	v_mul_f32_e32 v40, 0x3fb8aa3b, v3
	s_waitcnt vmcnt(0) lgkmcnt(0)
	v_mfma_f32_16x16x32_bf16 v[12:15], v[16:19], v[8:11], v[12:15]
	ds_read_b128 v[16:19], v38 offset:2304
	ds_read_b128 v[42:45], v38 offset:2368
	s_waitcnt lgkmcnt(1)
	v_mfma_f32_16x16x32_bf16 v[16:19], v[16:19], v[4:7], 0
	s_waitcnt lgkmcnt(0)
	v_mfma_f32_16x16x32_bf16 v[16:19], v[42:45], v[8:11], v[16:19]
	ds_read_b128 v[42:45], v38 offset:4608
	ds_read_b128 v[46:49], v38 offset:4672
	s_waitcnt lgkmcnt(1)
	v_mfma_f32_16x16x32_bf16 v[42:45], v[42:45], v[4:7], 0
	s_waitcnt lgkmcnt(0)
	v_mfma_f32_16x16x32_bf16 v[42:45], v[46:49], v[8:11], v[42:45]
	ds_read_b128 v[46:49], v38 offset:6912
	ds_read_b128 v[50:53], v38 offset:6976
	s_waitcnt lgkmcnt(1)
	v_mfma_f32_16x16x32_bf16 v[46:49], v[46:49], v[4:7], 0
	s_waitcnt lgkmcnt(0)
	v_mfma_f32_16x16x32_bf16 v[46:49], v[50:53], v[8:11], v[46:49]
	ds_read_b128 v[50:53], v38 offset:9216
	ds_read_b128 v[54:57], v38 offset:9280
	s_waitcnt lgkmcnt(1)
	v_mfma_f32_16x16x32_bf16 v[50:53], v[50:53], v[4:7], 0
	s_waitcnt lgkmcnt(0)
	v_mfma_f32_16x16x32_bf16 v[50:53], v[54:57], v[8:11], v[50:53]
	ds_read_b128 v[54:57], v38 offset:11520
	ds_read_b128 v[58:61], v38 offset:11584
	s_waitcnt lgkmcnt(1)
	v_mfma_f32_16x16x32_bf16 v[54:57], v[54:57], v[4:7], 0
	s_waitcnt lgkmcnt(0)
	v_mfma_f32_16x16x32_bf16 v[54:57], v[58:61], v[8:11], v[54:57]
	ds_read_b128 v[58:61], v38 offset:13824
	ds_read_b128 v[62:65], v38 offset:13888
	s_waitcnt lgkmcnt(1)
	v_mfma_f32_16x16x32_bf16 v[58:61], v[58:61], v[4:7], 0
	s_waitcnt lgkmcnt(0)
	v_mfma_f32_16x16x32_bf16 v[58:61], v[62:65], v[8:11], v[58:61]
	ds_read_b128 v[62:65], v38 offset:16128
	ds_read_b128 v[66:69], v38 offset:16192
	s_waitcnt lgkmcnt(1)
	v_mfma_f32_16x16x32_bf16 v[62:65], v[62:65], v[4:7], 0
	s_waitcnt lgkmcnt(0)
	v_mfma_f32_16x16x32_bf16 v[62:65], v[66:69], v[8:11], v[62:65]
	ds_read_b128 v[66:69], v38 offset:18432
	ds_read_b128 v[70:73], v38 offset:18496
	s_mov_b32 s8, 0xf149f2ca
	v_add_u32_e32 v80, 0x5800, v39
	v_add_u32_e32 v81, 0x8000, v39
	s_waitcnt lgkmcnt(1)
	v_mfma_f32_16x16x32_bf16 v[4:7], v[66:69], v[4:7], 0
	v_add_u32_e32 v82, 0x9800, v39
	s_waitcnt lgkmcnt(0)
	v_mfma_f32_16x16x32_bf16 v[4:7], v[70:73], v[8:11], v[4:7]
	v_mul_f32_e64 v8, v0, v160
	v_mul_f32_e64 v9, v0, v161
	v_sub_f32_e32 v3, v12, v9
	v_sub_f32_e32 v10, v13, v9
	v_fmac_f32_e32 v3, 0, v0
	v_fmac_f32_e32 v10, 0x3fb8aa3b, v1
	v_sub_f32_e32 v11, v14, v9
	v_sub_f32_e32 v12, v15, v9
	v_cndmask_b32_e64 v3, v214, v3, s[40:41]
	v_cndmask_b32_e64 v1, v214, v10, s[42:43]
	v_fmac_f32_e32 v11, 2.0, v0
	v_fmac_f32_e32 v12, 0x40400000, v0
	v_max3_f32 v10, v3, s8, v1
	v_cndmask_b32_e64 v11, v214, v11, s[44:45]
	v_cndmask_b32_e64 v12, v214, v12, s[0:1]
	v_sub_f32_e32 v13, v16, v9
	v_sub_f32_e32 v14, v17, v9
	v_max3_f32 v10, v10, v11, v12
	v_fmac_f32_e32 v13, 0x41800000, v0
	v_fmac_f32_e32 v14, 0x41880000, v0
	v_sub_f32_e32 v15, v18, v9
	v_sub_f32_e32 v16, v19, v9
	v_max3_f32 v10, v10, v13, v14
	v_fmac_f32_e32 v15, 0x41900000, v0
	v_fmac_f32_e32 v16, 0x41980000, v0
	v_sub_f32_e32 v17, v42, v9
	v_sub_f32_e32 v18, v43, v9
	v_max3_f32 v10, v10, v15, v16
	v_fmac_f32_e32 v17, 0x42000000, v0
	v_fmac_f32_e32 v18, 0x42040000, v0
	v_sub_f32_e32 v19, v44, v9
	v_sub_f32_e32 v32, v45, v9
	v_max3_f32 v10, v10, v17, v18
	v_fmac_f32_e32 v19, 0x42080000, v0
	v_fmac_f32_e32 v32, 0x420c0000, v0
	v_sub_f32_e32 v33, v46, v9
	v_sub_f32_e32 v42, v47, v9
	v_max3_f32 v10, v10, v19, v32
	v_fmac_f32_e32 v33, 0x42400000, v0
	v_fmac_f32_e32 v42, 0x42440000, v0
	v_sub_f32_e32 v43, v48, v9
	v_sub_f32_e32 v44, v49, v9
	v_max3_f32 v10, v10, v33, v42
	v_fmac_f32_e32 v43, 0x42480000, v0
	v_fmac_f32_e32 v44, 0x424c0000, v0
	v_sub_f32_e32 v45, v50, v9
	v_sub_f32_e32 v46, v51, v9
	v_max3_f32 v10, v10, v43, v44
	v_fmac_f32_e32 v45, 0x42800000, v0
	v_fmac_f32_e32 v46, 0x42820000, v0
	v_sub_f32_e32 v47, v52, v9
	v_sub_f32_e32 v48, v53, v9
	v_max3_f32 v10, v10, v45, v46
	v_fmac_f32_e32 v47, 0x42840000, v0
	v_fmac_f32_e32 v48, 0x42860000, v0
	v_sub_f32_e32 v49, v54, v9
	v_sub_f32_e32 v50, v55, v9
	v_max3_f32 v10, v10, v47, v48
	v_fmac_f32_e32 v49, 0x42a00000, v0
	v_fmac_f32_e32 v50, 0x42a20000, v0
	v_sub_f32_e32 v51, v56, v9
	v_sub_f32_e32 v52, v57, v9
	v_max3_f32 v10, v10, v49, v50
	v_fmac_f32_e32 v51, 0x42a40000, v0
	v_fmac_f32_e32 v52, 0x42a60000, v0
	v_sub_f32_e32 v53, v58, v9
	v_sub_f32_e32 v54, v59, v9
	v_max3_f32 v10, v10, v51, v52
	v_fmac_f32_e32 v53, 0x42c00000, v0
	v_fmac_f32_e32 v54, 0x42c20000, v0
	v_sub_f32_e32 v55, v60, v9
	v_sub_f32_e32 v56, v61, v9
	v_max3_f32 v10, v10, v53, v54
	v_fmac_f32_e32 v55, 0x42c40000, v0
	v_fmac_f32_e32 v56, 0x42c60000, v0
	v_sub_f32_e32 v57, v62, v9
	v_sub_f32_e32 v58, v63, v9
	v_sub_f32_e32 v6, v6, v9
	v_max3_f32 v10, v10, v55, v56
	v_fmac_f32_e32 v57, 0x42e00000, v0
	v_fmac_f32_e32 v58, 0x42e20000, v0
	v_sub_f32_e32 v59, v64, v9
	v_sub_f32_e32 v60, v65, v9
	v_sub_f32_e32 v4, v4, v9
	v_sub_f32_e32 v5, v5, v9
	v_fmac_f32_e32 v6, 0x43020000, v0
	v_max3_f32 v10, v10, v57, v58
	v_fmac_f32_e32 v59, 0x42e40000, v0
	v_fmac_f32_e32 v60, 0x42e60000, v0
	v_fmac_f32_e32 v4, 0x43000000, v0
	v_fmac_f32_e32 v5, 0x43010000, v0
	v_cndmask_b32_e64 v0, v214, v6, s[50:51]
	v_sub_f32_e32 v6, v7, v9
	v_max3_f32 v10, v10, v59, v60
	v_cndmask_b32_e64 v4, v4, v214, s[40:41]
	v_cndmask_b32_e64 v5, v214, v5, s[4:5]
	v_add_f32_e32 v6, v8, v6
	v_max3_f32 v10, v10, v4, v5
	v_cndmask_b32_e64 v6, v214, v6, s[52:53]
	v_max3_f32 v7, v10, v0, v6
	ds_bpermute_b32 v8, v25, v7
	s_waitcnt lgkmcnt(0)
	v_max_f32_e32 v8, v8, v8
	v_max_f32_e32 v7, v7, v8
	ds_bpermute_b32 v8, v34, v7
	s_waitcnt lgkmcnt(0)
	v_max3_f32 v41, v7, v8, v40
	v_sub_f32_e32 v3, v3, v41
	v_exp_f32_e32 v3, v3
	v_sub_f32_e32 v1, v1, v41
	v_exp_f32_e32 v1, v1
	v_sub_f32_e32 v8, v11, v41
	v_exp_f32_e32 v8, v8
	v_sub_f32_e32 v9, v12, v41
	v_exp_f32_e32 v9, v9
	v_sub_f32_e32 v10, v13, v41
	v_add_f32_e32 v7, 0, v3
	v_exp_f32_e32 v10, v10
	v_sub_f32_e32 v11, v14, v41
	v_add_f32_e32 v7, v1, v7
	v_exp_f32_e32 v11, v11
	v_sub_f32_e32 v12, v15, v41
	v_add_f32_e32 v7, v8, v7
	v_exp_f32_e32 v12, v12
	v_sub_f32_e32 v13, v16, v41
	v_add_f32_e32 v7, v9, v7
	v_exp_f32_e32 v13, v13
	v_sub_f32_e32 v14, v17, v41
	v_add_f32_e32 v7, v10, v7
	v_exp_f32_e32 v61, v14
	v_sub_f32_e32 v14, v18, v41
	v_add_f32_e32 v7, v11, v7
	v_exp_f32_e32 v62, v14
	v_sub_f32_e32 v14, v19, v41
	v_add_f32_e32 v7, v12, v7
	v_exp_f32_e32 v63, v14
	v_sub_f32_e32 v14, v32, v41
	v_add_f32_e32 v7, v13, v7
	v_exp_f32_e32 v32, v14
	v_sub_f32_e32 v14, v33, v41
	v_add_f32_e32 v7, v61, v7
	v_exp_f32_e32 v33, v14
	v_sub_f32_e32 v14, v42, v41
	v_add_f32_e32 v7, v62, v7
	v_exp_f32_e32 v64, v14
	v_sub_f32_e32 v14, v43, v41
	v_add_f32_e32 v7, v63, v7
	v_exp_f32_e32 v65, v14
	v_sub_f32_e32 v14, v44, v41
	v_add_f32_e32 v7, v32, v7
	v_exp_f32_e32 v66, v14
	v_sub_f32_e32 v14, v45, v41
	v_add_f32_e32 v7, v33, v7
	v_exp_f32_e32 v67, v14
	v_sub_f32_e32 v14, v46, v41
	v_add_f32_e32 v7, v64, v7
	v_exp_f32_e32 v68, v14
	v_sub_f32_e32 v14, v47, v41
	v_add_f32_e32 v7, v65, v7
	v_exp_f32_e32 v69, v14
	v_sub_f32_e32 v14, v48, v41
	v_add_f32_e32 v7, v66, v7
	v_exp_f32_e32 v70, v14
	v_sub_f32_e32 v14, v49, v41
	v_add_f32_e32 v7, v67, v7
	v_exp_f32_e32 v71, v14
	v_sub_f32_e32 v14, v50, v41
	v_add_f32_e32 v7, v68, v7
	v_exp_f32_e32 v72, v14
	v_sub_f32_e32 v14, v51, v41
	v_add_f32_e32 v7, v69, v7
	v_exp_f32_e32 v73, v14
	v_sub_f32_e32 v14, v52, v41
	v_add_f32_e32 v7, v70, v7
	v_exp_f32_e32 v52, v14
	v_sub_f32_e32 v14, v53, v41
	v_add_f32_e32 v7, v71, v7
	v_exp_f32_e32 v53, v14
	v_sub_f32_e32 v14, v54, v41
	v_add_f32_e32 v7, v72, v7
	v_exp_f32_e32 v54, v14
	v_sub_f32_e32 v14, v55, v41
	v_add_f32_e32 v7, v73, v7
	v_exp_f32_e32 v55, v14
	v_sub_f32_e32 v14, v56, v41
	v_add_f32_e32 v7, v52, v7
	v_exp_f32_e32 v56, v14
	v_sub_f32_e32 v14, v57, v41
	v_add_f32_e32 v7, v53, v7
	v_exp_f32_e32 v57, v14
	v_sub_f32_e32 v14, v58, v41
	v_add_f32_e32 v7, v54, v7
	v_exp_f32_e32 v58, v14
	v_sub_f32_e32 v14, v59, v41
	v_add_f32_e32 v7, v55, v7
	v_exp_f32_e32 v59, v14
	v_sub_f32_e32 v14, v60, v41
	v_add_f32_e32 v7, v56, v7
	v_exp_f32_e32 v60, v14
	v_sub_f32_e32 v4, v4, v41
	v_add_f32_e32 v7, v57, v7
	v_exp_f32_e32 v74, v4
	v_sub_f32_e32 v5, v5, v41
	v_add_f32_e32 v7, v58, v7
	v_exp_f32_e32 v75, v5
	v_sub_f32_e32 v0, v0, v41
	v_add_f32_e32 v7, v59, v7
	v_exp_f32_e32 v77, v0
	v_add_f32_e32 v7, v60, v7
	v_add_f32_e32 v4, v74, v7
	v_add_f32_e32 v4, v75, v4
	v_add_f32_e32 v0, v77, v4
	v_sub_f32_e32 v4, v6, v41
	v_exp_f32_e32 v79, v4
	v_cvt_pk_bf16_f32 v5, v8, v9
	v_cvt_pk_bf16_f32 v6, v10, v11
	v_cvt_pk_bf16_f32 v7, v12, v13
	v_add_f32_e32 v0, v79, v0
	ds_bpermute_b32 v4, v25, v0
	ds_read2_b64 v[8:11], v80 offset0:64 offset1:68
	ds_read2_b64 v[16:19], v81 offset0:128 offset1:132
	ds_read2_b64 v[44:47], v82 offset0:32 offset1:36
	s_waitcnt lgkmcnt(3)
	v_add_f32_e32 v42, v0, v4
	v_add_u32_e32 v0, 0x6800, v39
	ds_read2_b64 v[12:15], v0 offset0:224 offset1:228
	ds_bpermute_b32 v43, v34, v42
	v_cvt_pk_bf16_f32 v4, v3, v1
	s_waitcnt lgkmcnt(4)
	s_nop 0
	v_mfma_f32_16x16x32_bf16 v[8:11], v[8:11], v[4:7], 0
	s_waitcnt lgkmcnt(1)
	v_mfma_f32_16x16x32_bf16 v[12:15], v[12:15], v[4:7], 0
	v_mfma_f32_16x16x32_bf16 v[16:19], v[16:19], v[4:7], 0
	v_mfma_f32_16x16x32_bf16 v[4:7], v[44:47], v[4:7], 0
	ds_read2_b64 v[48:51], v80 offset0:72 offset1:76
	v_cvt_pk_bf16_f32 v44, v61, v62
	v_cvt_pk_bf16_f32 v45, v63, v32
	v_cvt_pk_bf16_f32 v46, v33, v64
	v_cvt_pk_bf16_f32 v47, v65, v66
	s_waitcnt lgkmcnt(0)
	s_nop 0
	v_mfma_f32_16x16x32_bf16 v[8:11], v[48:51], v[44:47], v[8:11]
	ds_read2_b64 v[48:51], v0 offset0:232 offset1:236
	s_waitcnt lgkmcnt(0)
	v_mfma_f32_16x16x32_bf16 v[12:15], v[48:51], v[44:47], v[12:15]
	ds_read2_b64 v[48:51], v81 offset0:136 offset1:140
	s_waitcnt lgkmcnt(0)
	v_mfma_f32_16x16x32_bf16 v[16:19], v[48:51], v[44:47], v[16:19]
	ds_read2_b64 v[48:51], v82 offset0:40 offset1:44
	s_waitcnt lgkmcnt(0)
	v_mfma_f32_16x16x32_bf16 v[4:7], v[48:51], v[44:47], v[4:7]
	ds_read2_b64 v[48:51], v80 offset0:80 offset1:84
	v_cvt_pk_bf16_f32 v44, v67, v68
	v_cvt_pk_bf16_f32 v45, v69, v70
	v_cvt_pk_bf16_f32 v46, v71, v72
	v_cvt_pk_bf16_f32 v47, v73, v52
	s_waitcnt lgkmcnt(0)
	s_nop 0
	v_mfma_f32_16x16x32_bf16 v[8:11], v[48:51], v[44:47], v[8:11]
	ds_read2_b64 v[48:51], v0 offset0:240 offset1:244
	s_waitcnt lgkmcnt(0)
	v_mfma_f32_16x16x32_bf16 v[12:15], v[48:51], v[44:47], v[12:15]
	ds_read2_b64 v[48:51], v81 offset0:144 offset1:148
	s_waitcnt lgkmcnt(0)
	v_mfma_f32_16x16x32_bf16 v[16:19], v[48:51], v[44:47], v[16:19]
	ds_read2_b64 v[48:51], v82 offset0:48 offset1:52
	s_waitcnt lgkmcnt(0)
	v_mfma_f32_16x16x32_bf16 v[4:7], v[48:51], v[44:47], v[4:7]
	ds_read2_b64 v[48:51], v80 offset0:88 offset1:92
	v_cvt_pk_bf16_f32 v44, v53, v54
	v_cvt_pk_bf16_f32 v45, v55, v56
	v_cvt_pk_bf16_f32 v46, v57, v58
	v_cvt_pk_bf16_f32 v47, v59, v60
	s_waitcnt lgkmcnt(0)
	s_nop 0
	v_mfma_f32_16x16x32_bf16 v[8:11], v[48:51], v[44:47], v[8:11]
	ds_read2_b64 v[48:51], v0 offset0:248 offset1:252
	s_waitcnt lgkmcnt(0)
	v_mfma_f32_16x16x32_bf16 v[12:15], v[48:51], v[44:47], v[12:15]
	ds_read2_b64 v[48:51], v81 offset0:152 offset1:156
	s_waitcnt lgkmcnt(0)
	v_mfma_f32_16x16x32_bf16 v[48:51], v[48:51], v[44:47], v[16:19]
	s_nop 2
	ds_read2_b64 v[16:19], v82 offset0:56 offset1:60
	s_waitcnt lgkmcnt(0)
	v_mfma_f32_16x16x32_bf16 v[4:7], v[16:19], v[44:47], v[4:7]
	ds_read2_b64 v[16:19], v80 offset0:96 offset1:100
	v_cvt_pk_bf16_f32 v0, v74, v75
	v_cvt_pk_bf16_f32 v1, v77, v79
	v_mov_b32_e32 v3, v2
	ds_read2_b64 v[44:47], v82 offset0:64 offset1:68
	s_waitcnt lgkmcnt(1)
	v_mfma_f32_16x16x32_bf16 v[16:19], v[16:19], v[0:3], v[8:11]
	s_nop 2
	v_add_u32_e32 v8, 0x7000, v39
	ds_read2_b64 v[8:11], v8 offset1:4
	s_waitcnt lgkmcnt(1)
	v_mfma_f32_16x16x32_bf16 v[4:7], v[44:47], v[0:3], v[4:7]
	s_waitcnt lgkmcnt(0)
	v_mfma_f32_16x16x32_bf16 v[12:15], v[8:11], v[0:3], v[12:15]
	ds_read2_b64 v[8:11], v81 offset0:160 offset1:164
	s_waitcnt lgkmcnt(0)
	v_mfma_f32_16x16x32_bf16 v[8:11], v[8:11], v[0:3], v[48:51]
	s_and_saveexec_b64 s[8:9], s[54:55]
	s_cbranch_execz .LBB0_568
	v_lshlrev_b64 v[0:1], 12, v[30:31]
	v_lshl_add_u64 v[0:1], v[0:1], 0, s[6:7]
	v_or_b32_e32 v0, v0, v78
	v_readlane_b32 s6, v253, 53
	v_sub_f32_e32 v3, v40, v41
	v_lshlrev_b64 v[30:31], 1, v[0:1]
	v_readlane_b32 s7, v253, 54
	v_exp_f32_e32 v3, v3
	s_nop 0
	v_lshl_add_u64 v[0:1], s[6:7], 0, v[30:31]
	v_readlane_b32 s6, v251, 22
	v_readlane_b32 s7, v251, 23
	s_nop 1
	v_lshl_add_u64 v[32:33], s[6:7], 0, v[30:31]
	v_add_f32_e32 v30, v42, v43
	v_add_f32_e32 v3, v3, v30
	v_div_scale_f32 v30, s[6:7], v3, v3, 1.0
	v_rcp_f32_e32 v31, v30
	s_nop 0
	v_fma_f32 v40, -v30, v31, 1.0
	v_fmac_f32_e32 v31, v40, v31
	v_div_scale_f32 v40, vcc, 1.0, v3, 1.0
	v_mul_f32_e32 v41, v40, v31
	v_fma_f32 v42, -v30, v41, v40
	v_fmac_f32_e32 v41, v42, v31
	v_fma_f32 v30, -v30, v41, v40
	v_div_fmas_f32 v30, v30, v31, v41
	v_mbcnt_lo_u32_b32 v40, -1, 0
	v_mbcnt_hi_u32_b32 v40, -1, v40
	v_and_b32_e32 v40, 16, v40
	v_lshrrev_b32_e32 v41, 1, v40
	v_add_u32_e32 v40, v40, v41
	v_mov_b32_e32 v41, 0
	v_lshl_add_u64 v[32:33], v[40:41], 0, v[32:33]
	v_lshl_add_u64 v[0:1], v[40:41], 0, v[0:1]
	global_load_dwordx4 v[44:47], v[32:33], off
	global_load_dwordx4 v[48:51], v[32:33], off offset:64
	v_div_fixup_f32 v30, v30, v3, 1.0
	v_pk_mul_f32 v[18:19], v[30:31], v[18:19] op_sel_hi:[0,1]
	v_pk_mul_f32 v[16:17], v[30:31], v[16:17] op_sel_hi:[0,1]
	v_pk_mul_f32 v[14:15], v[30:31], v[14:15] op_sel_hi:[0,1]
	v_pk_mul_f32 v[12:13], v[30:31], v[12:13] op_sel_hi:[0,1]
	v_pk_mul_f32 v[10:11], v[30:31], v[10:11] op_sel_hi:[0,1]
	v_pk_mul_f32 v[8:9], v[30:31], v[8:9] op_sel_hi:[0,1]
	v_pk_mul_f32 v[6:7], v[30:31], v[6:7] op_sel_hi:[0,1]
	v_pk_mul_f32 v[4:5], v[30:31], v[4:5] op_sel_hi:[0,1]
	s_waitcnt vmcnt(0)
	v_permlane16_swap_b32 v44, v46
	v_permlane16_swap_b32 v45, v47
	v_permlane16_swap_b32 v48, v50
	v_permlane16_swap_b32 v49, v51
	s_nop 1
	v_lshlrev_b32_e32 v42, 16, v44
	v_and_b32_e32 v43, 0xffff0000, v44
	v_pk_mul_f32 v[16:17], v[16:17], v[42:43]
	v_lshlrev_b32_e32 v42, 16, v45
	v_and_b32_e32 v43, 0xffff0000, v45
	v_pk_mul_f32 v[18:19], v[18:19], v[42:43]
	v_cvt_pk_bf16_f32 v16, v16, v17
	v_cvt_pk_bf16_f32 v17, v18, v19
	v_lshlrev_b32_e32 v42, 16, v46
	v_and_b32_e32 v43, 0xffff0000, v46
	v_pk_mul_f32 v[12:13], v[12:13], v[42:43]
	v_lshlrev_b32_e32 v42, 16, v47
	v_and_b32_e32 v43, 0xffff0000, v47
	v_pk_mul_f32 v[14:15], v[14:15], v[42:43]
	v_cvt_pk_bf16_f32 v18, v12, v13
	v_cvt_pk_bf16_f32 v19, v14, v15
	v_lshlrev_b32_e32 v42, 16, v48
	v_and_b32_e32 v43, 0xffff0000, v48
	v_pk_mul_f32 v[8:9], v[8:9], v[42:43]
	v_lshlrev_b32_e32 v42, 16, v49
	v_and_b32_e32 v43, 0xffff0000, v49
	v_pk_mul_f32 v[10:11], v[10:11], v[42:43]
	v_cvt_pk_bf16_f32 v8, v8, v9
	v_cvt_pk_bf16_f32 v9, v10, v11
	v_lshlrev_b32_e32 v42, 16, v50
	v_and_b32_e32 v43, 0xffff0000, v50
	v_pk_mul_f32 v[4:5], v[4:5], v[42:43]
	v_lshlrev_b32_e32 v42, 16, v51
	v_and_b32_e32 v43, 0xffff0000, v51
	v_pk_mul_f32 v[6:7], v[6:7], v[42:43]
	v_cvt_pk_bf16_f32 v10, v4, v5
	v_cvt_pk_bf16_f32 v11, v6, v7
	v_permlane16_swap_b32 v16, v18
	v_permlane16_swap_b32 v17, v19
	global_store_dwordx4 v[0:1], v[16:19], off
	v_permlane16_swap_b32 v8, v10
	v_permlane16_swap_b32 v9, v11
	global_store_dwordx4 v[0:1], v[8:11], off offset:64
	s_nop 1
	s_branch .LBB0_568
